# removed per-segment s_setprio toggles from the GEMM K-loop (both wave halves at equal priority)
# speedup vs baseline: 1.0042x; 1.0042x over previous
; #define PG8_STAGE(bufoff, gbase, voff) do { _Pragma("unroll") for (int _i = 0; _i < 2; ++_i) \
;     __builtin_amdgcn_global_load_lds((const unsigned*)((const char*)(gbase) + (voff)[_i]), (LAS unsigned*)(lds + (bufoff) + ldsw + _i * 8192), 16, 0, 0); } while (0)
; #define PG8_LDA(dst, b, h) do { _Pragma("unroll") for (int m = 0; m < 4; ++m) _Pragma("unroll") for (int k = 0; k < 2; ++k) dst[m][k] = *(const LAS bf16x8*)(lds + PG8_SA(b, h) + aoff + m * 2048 + k * 1024); } while (0)
; #define PG8_LDB(dst, b, h) do { _Pragma("unroll") for (int n = 0; n < 2; ++n) _Pragma("unroll") for (int k = 0; k < 2; ++k) dst[n][k] = *(const LAS bf16x8*)(lds + PG8_SB(b, h) + boff + n * 2048 + k * 1024); } while (0)
; #define PG8_MMA(ai, bj, At, Bt) do { __builtin_amdgcn_s_setprio(1); _Pragma("unroll") for (int m = 0; m < 4; ++m) _Pragma("unroll") for (int n = 0; n < 2; ++n) _Pragma("unroll") for (int k = 0; k < 2; ++k) \
;     acc[ai][bj][m][n] = __builtin_amdgcn_mfma_f32_16x16x32_bf16(Bt[n][k], At[m][k], acc[ai][bj][m][n], 0, 0, 0); __builtin_amdgcn_s_setprio(0); } while (0)
; #define PG8_WAIT_V(n) asm volatile("s_waitcnt vmcnt(" #n ")" ::: "memory")
; #define PG8_WAIT_L(n) asm volatile("s_waitcnt lgkmcnt(" #n ")" ::: "memory")
; #define PG8_BAR __builtin_amdgcn_s_barrier()
; __device__ __forceinline__ void gemm_phase(const Ctx& cx, LAS unsigned char* lds, const GemmDesc& g) {
;     ...
;     for (int t = 0; t < nt; t += 2) {
;       const bool last = (t == nt - 2);
;       const char* a1 = ktile_ptr(cA1, cA2, t + 1, ksplit, kstepA);
;       const char* a2 = last ? ktile_ptr(nA1, nA2, 0, ksplit, kstepA) : ktile_ptr(cA1, cA2, t + 2, ksplit, kstepA);
;       const char* a3 = last ? ktile_ptr(nA1, nA2, 1, ksplit, kstepA) : ktile_ptr(cA1, cA2, t + 3, ksplit, kstepA);
;       const char* b2 = last ? nB : cB + (size_t)(t + 2) * kstepB; const char* b3 = b2 + kstepB;
;       PG8_LDB(B0, 0, 0); PG8_LDB(B1, 0, 1); PG8_SCHED; PG8_LDA(At, 0, 0); PG8_STAGE(PG8_SA(1, 1), a1 + hstepA, voffA);
;       PG8_WAIT_V(8); PG8_WAIT_L(0); PG8_BAR; PG8_MMA(0, 0, At, B0); PG8_MMA(0, 1, At, B1); PG8_BAR; PG8_SCHED;
;       PG8_LDA(At, 0, 1); PG8_STAGE(PG8_SB(0, 0), b2, voffB); PG8_STAGE(PG8_SB(0, 1), b2 + hstepB, voffB); PG8_STAGE(PG8_SA(0, 0), a2, voffA);
;       PG8_WAIT_V(8); PG8_WAIT_L(0); PG8_BAR; PG8_MMA(1, 0, At, B0); PG8_MMA(1, 1, At, B1); PG8_BAR; PG8_SCHED;
.LBB0_357:
	s_add_u32 s12, s60, s18
	s_addc_u32 s13, s61, s19
	s_add_u32 s16, s24, s16
	s_addc_u32 s17, s25, s17
	s_add_u32 s20, s12, s68
	s_addc_u32 s21, s13, s69
	s_add_u32 s52, s14, 0x100
	s_addc_u32 s53, s15, 0
	s_mov_b32 s6, 0
	s_add_i32 s7, s6, 1
	s_sub_i32 s14, s7, s41
	s_min_u32 s76, s7, s14
	s_cmp_lt_u32 s7, s41
	s_cselect_b32 s7, s9, s17
	s_cselect_b32 s54, s8, s16
	s_lshl_b64 s[14:15], s[76:77], s80
	s_add_u32 s55, s54, s14
	s_addc_u32 s73, s7, s15
	s_add_i32 s76, 0, 0x10000
	v_add_u32_e32 v96, s76, v252
	s_add_i32 vcc_lo, 0, 0x14000
	ds_read_b128 v[130:133], v96
	ds_read_b128 v[134:137], v96 offset:1024
	ds_read_b128 v[138:141], v96 offset:2048
	ds_read_b128 v[142:145], v96 offset:3072
	v_add_u32_e32 v96, vcc_lo, v252
	ds_read_b128 v[146:149], v96
	ds_read_b128 v[150:153], v96 offset:1024
	ds_read_b128 v[154:157], v96 offset:2048
	ds_read_b128 v[158:161], v96 offset:3072
	s_add_u32 s72, s55, s28
	s_addc_u32 s73, s73, s29
	v_lshl_add_u64 v[194:195], s[72:73], 0, v[210:211]
	s_add_i32 m0, s51, 0xc000
	ds_read_b128 v[162:165], v237
	ds_read_b128 v[166:169], v237 offset:1024
	ds_read_b128 v[170:173], v237 offset:2048
	ds_read_b128 v[174:177], v237 offset:3072
	ds_read_b128 v[178:181], v237 offset:4096
	ds_read_b128 v[182:185], v237 offset:5120
	ds_read_b128 v[186:189], v237 offset:6144
	ds_read_b128 v[190:193], v237 offset:7168
	global_load_lds_dwordx4 v[194:195], off
	v_lshl_add_u64 v[194:195], s[72:73], 0, v[212:213]
	s_add_i32 m0, s51, 0xe000
	s_nop 0
	global_load_lds_dwordx4 v[194:195], off
	s_waitcnt vmcnt(8)
	s_waitcnt lgkmcnt(0)
	s_barrier
	s_waitcnt lgkmcnt(0)
	v_mfma_f32_16x16x32_bf16 v[126:129], v[130:133], v[162:165], 0
	v_mfma_f32_16x16x32_bf16 v[126:129], v[134:137], v[166:169], v[126:129]
	s_add_i32 s54, s6, 2
	s_cmp_lt_u32 s54, s41
	v_mfma_f32_16x16x32_bf16 v[122:125], v[142:145], v[166:169], 0
	s_cselect_b64 s[14:15], -1, 0
	s_and_b64 s[58:59], s[14:15], exec
	v_mfma_f32_16x16x32_bf16 v[122:125], v[138:141], v[162:165], v[122:125]
	s_cselect_b32 s7, 0, s41
	s_sub_i32 s7, s6, s7
	v_mfma_f32_16x16x32_bf16 v[118:121], v[146:149], v[162:165], 0
	s_add_i32 s76, s7, 2
	s_and_b64 s[14:15], s[14:15], exec
	v_mfma_f32_16x16x32_bf16 v[118:121], v[150:153], v[166:169], v[118:121]
	s_cselect_b32 s7, s9, s17
	s_cselect_b32 s58, s8, s16
	v_mfma_f32_16x16x32_bf16 v[114:117], v[158:161], v[166:169], 0
	s_lshl_b64 s[14:15], s[76:77], s80
	s_add_u32 s72, s58, s14
	v_mfma_f32_16x16x32_bf16 v[114:117], v[154:157], v[162:165], v[114:117]
	s_addc_u32 s7, s7, s15
	s_add_i32 s14, s6, 3
	v_mfma_f32_16x16x32_bf16 v[98:101], v[154:157], v[170:173], 0
	s_cmp_lt_u32 s14, s41
	s_cselect_b64 s[14:15], -1, 0
	v_mfma_f32_16x16x32_bf16 v[98:101], v[158:161], v[174:177], v[98:101]
	s_and_b64 s[58:59], s[14:15], exec
	s_cselect_b32 s58, 0, s41
	v_mfma_f32_16x16x32_bf16 v[102:105], v[150:153], v[174:177], 0
	s_sub_i32 s58, s6, s58
	s_add_i32 s76, s58, 3
	v_mfma_f32_16x16x32_bf16 v[102:105], v[146:149], v[170:173], v[102:105]
	s_and_b64 s[14:15], s[14:15], exec
	s_cselect_b32 s58, s9, s17
	v_mfma_f32_16x16x32_bf16 v[106:109], v[138:141], v[170:173], 0
	s_cselect_b32 s59, s8, s16
	s_lshl_b64 s[14:15], s[76:77], s80
	v_mfma_f32_16x16x32_bf16 v[106:109], v[142:145], v[174:177], v[106:109]
	s_add_u32 s59, s59, s14
	s_addc_u32 s58, s58, s15
	v_mfma_f32_16x16x32_bf16 v[110:113], v[134:137], v[174:177], 0
	s_cmp_eq_u32 s39, s6
	s_cselect_b32 s15, s13, s7
	v_mfma_f32_16x16x32_bf16 v[110:113], v[130:133], v[170:173], v[110:113]
	s_cselect_b32 s14, s12, s72
	s_cselect_b32 s7, s21, s58
	v_mfma_f32_16x16x32_bf16 v[92:95], v[130:133], v[178:181], 0
	s_cselect_b32 s6, s20, s59
	s_cselect_b32 s59, s97, s53
	v_mfma_f32_16x16x32_bf16 v[92:95], v[134:137], v[182:185], v[92:95]
	s_cselect_b32 s58, s96, s52
	s_mov_b32 s76, 0x10000
	v_mfma_f32_16x16x32_bf16 v[88:91], v[142:145], v[182:185], 0
	v_mfma_f32_16x16x32_bf16 v[88:91], v[138:141], v[178:181], v[88:91]
	v_mfma_f32_16x16x32_bf16 v[84:87], v[146:149], v[178:181], 0
	v_mfma_f32_16x16x32_bf16 v[84:87], v[150:153], v[182:185], v[84:87]
	v_mfma_f32_16x16x32_bf16 v[80:83], v[158:161], v[182:185], 0
	v_mfma_f32_16x16x32_bf16 v[80:83], v[154:157], v[178:181], v[80:83]
	v_mfma_f32_16x16x32_bf16 v[64:67], v[154:157], v[186:189], 0
	v_mfma_f32_16x16x32_bf16 v[64:67], v[158:161], v[190:193], v[64:67]
	v_mfma_f32_16x16x32_bf16 v[68:71], v[150:153], v[190:193], 0
	v_mfma_f32_16x16x32_bf16 v[68:71], v[146:149], v[186:189], v[68:71]
	v_mfma_f32_16x16x32_bf16 v[72:75], v[138:141], v[186:189], 0
	v_mfma_f32_16x16x32_bf16 v[72:75], v[142:145], v[190:193], v[72:75]
	v_mfma_f32_16x16x32_bf16 v[76:79], v[134:137], v[190:193], 0
	v_mfma_f32_16x16x32_bf16 v[76:79], v[130:133], v[186:189], v[76:79]
	s_barrier
	s_add_i32 s55, s76, s36
	v_lshl_add_u64 v[194:195], s[58:59], 0, v[216:217]
	s_mov_b32 m0, s55
	ds_read_b128 v[162:165], v237 offset:16384
	ds_read_b128 v[166:169], v237 offset:17408
	ds_read_b128 v[170:173], v237 offset:18432
	ds_read_b128 v[174:177], v237 offset:19456
	ds_read_b128 v[178:181], v237 offset:20480
	ds_read_b128 v[182:185], v237 offset:21504
	ds_read_b128 v[186:189], v237 offset:22528
	ds_read_b128 v[190:193], v237 offset:23552
	global_load_lds_dwordx4 v[194:195], off
	s_add_i32 m0, s55, 0x2000
	v_lshl_add_u64 v[196:197], s[58:59], 0, v[214:215]
	s_add_u32 s58, s58, s30
	s_addc_u32 s59, s59, s31
	s_add_i32 s55, vcc_lo, s36
	global_load_lds_dwordx4 v[196:197], off
	v_lshl_add_u64 v[198:199], s[58:59], 0, v[216:217]
	s_mov_b32 m0, s55
	v_lshl_add_u64 v[200:201], s[58:59], 0, v[214:215]
	global_load_lds_dwordx4 v[198:199], off
	s_add_i32 m0, s55, 0x2000
	v_lshl_add_u64 v[202:203], s[14:15], 0, v[210:211]
	global_load_lds_dwordx4 v[200:201], off
	s_mov_b32 m0, s51
	s_nop 0
	global_load_lds_dwordx4 v[202:203], off
	v_lshl_add_u64 v[202:203], s[14:15], 0, v[212:213]
	s_mov_b32 m0, s43
	s_nop 0
	global_load_lds_dwordx4 v[202:203], off
	s_waitcnt vmcnt(8)
	s_waitcnt lgkmcnt(0)
	s_barrier
; #define PG8_STAGE(bufoff, gbase, voff) do { _Pragma("unroll") for (int _i = 0; _i < 2; ++_i) \
;     __builtin_amdgcn_global_load_lds((const unsigned*)((const char*)(gbase) + (voff)[_i]), (LAS unsigned*)(lds + (bufoff) + ldsw + _i * 8192), 16, 0, 0); } while (0)
; #define PG8_LDA(dst, b, h) do { _Pragma("unroll") for (int m = 0; m < 4; ++m) _Pragma("unroll") for (int k = 0; k < 2; ++k) dst[m][k] = *(const LAS bf16x8*)(lds + PG8_SA(b, h) + aoff + m * 2048 + k * 1024); } while (0)
; #define PG8_LDB(dst, b, h) do { _Pragma("unroll") for (int n = 0; n < 2; ++n) _Pragma("unroll") for (int k = 0; k < 2; ++k) dst[n][k] = *(const LAS bf16x8*)(lds + PG8_SB(b, h) + boff + n * 2048 + k * 1024); } while (0)
; #define PG8_MMA(ai, bj, At, Bt) do { __builtin_amdgcn_s_setprio(1); _Pragma("unroll") for (int m = 0; m < 4; ++m) _Pragma("unroll") for (int n = 0; n < 2; ++n) _Pragma("unroll") for (int k = 0; k < 2; ++k) \
;     acc[ai][bj][m][n] = __builtin_amdgcn_mfma_f32_16x16x32_bf16(Bt[n][k], At[m][k], acc[ai][bj][m][n], 0, 0, 0); __builtin_amdgcn_s_setprio(0); } while (0)
; #define PG8_WAIT_V(n) asm volatile("s_waitcnt vmcnt(" #n ")" ::: "memory")
; #define PG8_WAIT_L(n) asm volatile("s_waitcnt lgkmcnt(" #n ")" ::: "memory")
; #define PG8_BAR __builtin_amdgcn_s_barrier()
; #define PG8_SCHED __builtin_amdgcn_sched_barrier(0)
; __device__ __forceinline__ void gemm_phase(const Ctx& cx, LAS unsigned char* lds, const GemmDesc& g) {
;     ...
;       PG8_LDB(B0, 0, 0); PG8_LDB(B1, 0, 1); PG8_SCHED; PG8_LDA(At, 0, 0); PG8_STAGE(PG8_SA(1, 1), a1 + hstepA, voffA);
;       PG8_WAIT_V(8); PG8_WAIT_L(0); PG8_BAR; PG8_MMA(0, 0, At, B0); PG8_MMA(0, 1, At, B1); PG8_BAR; PG8_SCHED;
;       PG8_LDA(At, 0, 1); PG8_STAGE(PG8_SB(0, 0), b2, voffB); PG8_STAGE(PG8_SB(0, 1), b2 + hstepB, voffB); PG8_STAGE(PG8_SA(0, 0), a2, voffA);
;       PG8_WAIT_V(8); PG8_WAIT_L(0); PG8_BAR; PG8_MMA(1, 0, At, B0); PG8_MMA(1, 1, At, B1); PG8_BAR; PG8_SCHED;
	s_waitcnt lgkmcnt(0)
	v_mfma_f32_16x16x32_bf16 v[60:63], v[130:133], v[162:165], 0
	v_mfma_f32_16x16x32_bf16 v[60:63], v[134:137], v[166:169], v[60:63]
	v_mfma_f32_16x16x32_bf16 v[56:59], v[142:145], v[166:169], 0
	v_mfma_f32_16x16x32_bf16 v[56:59], v[138:141], v[162:165], v[56:59]
	v_mfma_f32_16x16x32_bf16 v[52:55], v[146:149], v[162:165], 0
	v_mfma_f32_16x16x32_bf16 v[52:55], v[150:153], v[166:169], v[52:55]
	v_mfma_f32_16x16x32_bf16 v[48:51], v[158:161], v[166:169], 0
	v_mfma_f32_16x16x32_bf16 v[48:51], v[154:157], v[162:165], v[48:51]
	v_mfma_f32_16x16x32_bf16 v[32:35], v[154:157], v[170:173], 0
	v_mfma_f32_16x16x32_bf16 v[32:35], v[158:161], v[174:177], v[32:35]
	v_mfma_f32_16x16x32_bf16 v[36:39], v[150:153], v[174:177], 0
	v_mfma_f32_16x16x32_bf16 v[36:39], v[146:149], v[170:173], v[36:39]
	v_mfma_f32_16x16x32_bf16 v[40:43], v[138:141], v[170:173], 0
	v_mfma_f32_16x16x32_bf16 v[40:43], v[142:145], v[174:177], v[40:43]
	v_mfma_f32_16x16x32_bf16 v[44:47], v[134:137], v[174:177], 0
	v_mfma_f32_16x16x32_bf16 v[44:47], v[130:133], v[170:173], v[44:47]
	v_mfma_f32_16x16x32_bf16 v[28:31], v[130:133], v[178:181], 0
	v_mfma_f32_16x16x32_bf16 v[28:31], v[134:137], v[182:185], v[28:31]
	v_mfma_f32_16x16x32_bf16 v[24:27], v[142:145], v[182:185], 0
	v_mfma_f32_16x16x32_bf16 v[24:27], v[138:141], v[178:181], v[24:27]
	v_mfma_f32_16x16x32_bf16 v[20:23], v[146:149], v[178:181], 0
	v_mfma_f32_16x16x32_bf16 v[20:23], v[150:153], v[182:185], v[20:23]
	v_mfma_f32_16x16x32_bf16 v[16:19], v[158:161], v[182:185], 0
	v_mfma_f32_16x16x32_bf16 v[16:19], v[154:157], v[178:181], v[16:19]
	v_mfma_f32_16x16x32_bf16 v[0:3], v[154:157], v[186:189], 0
	v_mfma_f32_16x16x32_bf16 v[0:3], v[158:161], v[190:193], v[0:3]
	v_mfma_f32_16x16x32_bf16 v[4:7], v[150:153], v[190:193], 0
	v_mfma_f32_16x16x32_bf16 v[4:7], v[146:149], v[186:189], v[4:7]
	v_mfma_f32_16x16x32_bf16 v[8:11], v[138:141], v[186:189], 0
	v_mfma_f32_16x16x32_bf16 v[8:11], v[142:145], v[190:193], v[8:11]
	v_mfma_f32_16x16x32_bf16 v[12:15], v[134:137], v[190:193], 0
	v_mfma_f32_16x16x32_bf16 v[12:15], v[130:133], v[186:189], v[12:15]
	s_barrier
	s_branch .Lk_p2
.LBB0_358:
	s_add_i32 s7, s6, 1
	s_sub_i32 s14, s7, s41
	s_min_u32 s76, s7, s14
	s_cmp_lt_u32 s7, s41
	s_cselect_b32 s7, s9, s17
	s_cselect_b32 s54, s8, s16
	s_lshl_b64 s[14:15], s[76:77], s80
	s_add_u32 s55, s54, s14
	s_addc_u32 s73, s7, s15
	s_add_i32 s76, 0, 0x10000
	v_add_u32_e32 v96, s76, v252
	s_add_i32 vcc_lo, 0, 0x14000
	ds_read_b128 v[130:133], v96
	ds_read_b128 v[134:137], v96 offset:1024
	ds_read_b128 v[138:141], v96 offset:2048
	ds_read_b128 v[142:145], v96 offset:3072
	v_add_u32_e32 v96, vcc_lo, v252
	ds_read_b128 v[146:149], v96
	ds_read_b128 v[150:153], v96 offset:1024
	ds_read_b128 v[154:157], v96 offset:2048
	ds_read_b128 v[158:161], v96 offset:3072
	s_add_u32 s72, s55, s28
	s_addc_u32 s73, s73, s29
	v_lshl_add_u64 v[194:195], s[72:73], 0, v[210:211]
	s_add_i32 m0, s51, 0xc000
	ds_read_b128 v[162:165], v237
	ds_read_b128 v[166:169], v237 offset:1024
	ds_read_b128 v[170:173], v237 offset:2048
	ds_read_b128 v[174:177], v237 offset:3072
	ds_read_b128 v[178:181], v237 offset:4096
	ds_read_b128 v[182:185], v237 offset:5120
	ds_read_b128 v[186:189], v237 offset:6144
	ds_read_b128 v[190:193], v237 offset:7168
	global_load_lds_dwordx4 v[194:195], off
	v_lshl_add_u64 v[194:195], s[72:73], 0, v[212:213]
	s_add_i32 m0, s51, 0xe000
	s_nop 0
	global_load_lds_dwordx4 v[194:195], off
	s_waitcnt vmcnt(8)
	s_waitcnt lgkmcnt(0)
	s_barrier
	s_waitcnt lgkmcnt(0)
	v_mfma_f32_16x16x32_bf16 v[126:129], v[130:133], v[162:165], v[126:129]
	v_mfma_f32_16x16x32_bf16 v[126:129], v[134:137], v[166:169], v[126:129]
	s_add_i32 s54, s6, 2
	s_cmp_lt_u32 s54, s41
	v_mfma_f32_16x16x32_bf16 v[122:125], v[142:145], v[166:169], v[122:125]
	s_cselect_b64 s[14:15], -1, 0
	s_and_b64 s[58:59], s[14:15], exec
	v_mfma_f32_16x16x32_bf16 v[122:125], v[138:141], v[162:165], v[122:125]
	s_cselect_b32 s7, 0, s41
	s_sub_i32 s7, s6, s7
	v_mfma_f32_16x16x32_bf16 v[118:121], v[146:149], v[162:165], v[118:121]
	s_add_i32 s76, s7, 2
	s_and_b64 s[14:15], s[14:15], exec
	v_mfma_f32_16x16x32_bf16 v[118:121], v[150:153], v[166:169], v[118:121]
	s_cselect_b32 s7, s9, s17
	s_cselect_b32 s58, s8, s16
	v_mfma_f32_16x16x32_bf16 v[114:117], v[158:161], v[166:169], v[114:117]
	s_lshl_b64 s[14:15], s[76:77], s80
	s_add_u32 s72, s58, s14
	v_mfma_f32_16x16x32_bf16 v[114:117], v[154:157], v[162:165], v[114:117]
	s_addc_u32 s7, s7, s15
	s_add_i32 s14, s6, 3
	v_mfma_f32_16x16x32_bf16 v[98:101], v[154:157], v[170:173], v[98:101]
	s_cmp_lt_u32 s14, s41
	s_cselect_b64 s[14:15], -1, 0
	v_mfma_f32_16x16x32_bf16 v[98:101], v[158:161], v[174:177], v[98:101]
	s_and_b64 s[58:59], s[14:15], exec
	s_cselect_b32 s58, 0, s41
	v_mfma_f32_16x16x32_bf16 v[102:105], v[150:153], v[174:177], v[102:105]
	s_sub_i32 s58, s6, s58
	s_add_i32 s76, s58, 3
	v_mfma_f32_16x16x32_bf16 v[102:105], v[146:149], v[170:173], v[102:105]
	s_and_b64 s[14:15], s[14:15], exec
	s_cselect_b32 s58, s9, s17
	v_mfma_f32_16x16x32_bf16 v[106:109], v[138:141], v[170:173], v[106:109]
	s_cselect_b32 s59, s8, s16
	s_lshl_b64 s[14:15], s[76:77], s80
	v_mfma_f32_16x16x32_bf16 v[106:109], v[142:145], v[174:177], v[106:109]
	s_add_u32 s59, s59, s14
	s_addc_u32 s58, s58, s15
	v_mfma_f32_16x16x32_bf16 v[110:113], v[134:137], v[174:177], v[110:113]
	s_cmp_eq_u32 s39, s6
	s_cselect_b32 s15, s13, s7
	v_mfma_f32_16x16x32_bf16 v[110:113], v[130:133], v[170:173], v[110:113]
	s_cselect_b32 s14, s12, s72
	s_cselect_b32 s7, s21, s58
	v_mfma_f32_16x16x32_bf16 v[92:95], v[130:133], v[178:181], v[92:95]
	s_cselect_b32 s6, s20, s59
	s_cselect_b32 s59, s97, s53
	v_mfma_f32_16x16x32_bf16 v[92:95], v[134:137], v[182:185], v[92:95]
	s_cselect_b32 s58, s96, s52
	s_mov_b32 s76, 0x10000
	v_mfma_f32_16x16x32_bf16 v[88:91], v[142:145], v[182:185], v[88:91]
	v_mfma_f32_16x16x32_bf16 v[88:91], v[138:141], v[178:181], v[88:91]
	v_mfma_f32_16x16x32_bf16 v[84:87], v[146:149], v[178:181], v[84:87]
	v_mfma_f32_16x16x32_bf16 v[84:87], v[150:153], v[182:185], v[84:87]
	v_mfma_f32_16x16x32_bf16 v[80:83], v[158:161], v[182:185], v[80:83]
	v_mfma_f32_16x16x32_bf16 v[80:83], v[154:157], v[178:181], v[80:83]
	v_mfma_f32_16x16x32_bf16 v[64:67], v[154:157], v[186:189], v[64:67]
	v_mfma_f32_16x16x32_bf16 v[64:67], v[158:161], v[190:193], v[64:67]
	v_mfma_f32_16x16x32_bf16 v[68:71], v[150:153], v[190:193], v[68:71]
	v_mfma_f32_16x16x32_bf16 v[68:71], v[146:149], v[186:189], v[68:71]
	v_mfma_f32_16x16x32_bf16 v[72:75], v[138:141], v[186:189], v[72:75]
	v_mfma_f32_16x16x32_bf16 v[72:75], v[142:145], v[190:193], v[72:75]
	v_mfma_f32_16x16x32_bf16 v[76:79], v[134:137], v[190:193], v[76:79]
	v_mfma_f32_16x16x32_bf16 v[76:79], v[130:133], v[186:189], v[76:79]
	s_barrier
; #define PG8_STAGE(bufoff, gbase, voff) do { _Pragma("unroll") for (int _i = 0; _i < 2; ++_i) \
;     __builtin_amdgcn_global_load_lds((const unsigned*)((const char*)(gbase) + (voff)[_i]), (LAS unsigned*)(lds + (bufoff) + ldsw + _i * 8192), 16, 0, 0); } while (0)
; #define PG8_LDA(dst, b, h) do { _Pragma("unroll") for (int m = 0; m < 4; ++m) _Pragma("unroll") for (int k = 0; k < 2; ++k) dst[m][k] = *(const LAS bf16x8*)(lds + PG8_SA(b, h) + aoff + m * 2048 + k * 1024); } while (0)
; #define PG8_LDB(dst, b, h) do { _Pragma("unroll") for (int n = 0; n < 2; ++n) _Pragma("unroll") for (int k = 0; k < 2; ++k) dst[n][k] = *(const LAS bf16x8*)(lds + PG8_SB(b, h) + boff + n * 2048 + k * 1024); } while (0)
; #define PG8_MMA(ai, bj, At, Bt) do { __builtin_amdgcn_s_setprio(1); _Pragma("unroll") for (int m = 0; m < 4; ++m) _Pragma("unroll") for (int n = 0; n < 2; ++n) _Pragma("unroll") for (int k = 0; k < 2; ++k) \
;     acc[ai][bj][m][n] = __builtin_amdgcn_mfma_f32_16x16x32_bf16(Bt[n][k], At[m][k], acc[ai][bj][m][n], 0, 0, 0); __builtin_amdgcn_s_setprio(0); } while (0)
; #define PG8_WAIT_V(n) asm volatile("s_waitcnt vmcnt(" #n ")" ::: "memory")
; #define PG8_WAIT_L(n) asm volatile("s_waitcnt lgkmcnt(" #n ")" ::: "memory")
; #define PG8_BAR __builtin_amdgcn_s_barrier()
; #define PG8_SCHED __builtin_amdgcn_sched_barrier(0)
; __device__ __forceinline__ void gemm_phase(const Ctx& cx, LAS unsigned char* lds, const GemmDesc& g) {
;     ...
;       PG8_LDA(At, 0, 1); PG8_STAGE(PG8_SB(0, 0), b2, voffB); PG8_STAGE(PG8_SB(0, 1), b2 + hstepB, voffB); PG8_STAGE(PG8_SA(0, 0), a2, voffA);
;       PG8_WAIT_V(8); PG8_WAIT_L(0); PG8_BAR; PG8_MMA(1, 0, At, B0); PG8_MMA(1, 1, At, B1); PG8_BAR; PG8_SCHED;
;       PG8_LDB(B0, 1, 0); PG8_LDB(B1, 1, 1); PG8_SCHED; PG8_LDA(At, 1, 0); PG8_STAGE(PG8_SA(0, 1), a2 + hstepA, voffA);
;       PG8_WAIT_V(8); PG8_WAIT_L(0); PG8_BAR; PG8_MMA(0, 0, At, B0); PG8_MMA(0, 1, At, B1); PG8_BAR; PG8_SCHED;
	s_add_i32 s55, s76, s36
	v_lshl_add_u64 v[194:195], s[58:59], 0, v[216:217]
	s_mov_b32 m0, s55
	ds_read_b128 v[162:165], v237 offset:16384
	ds_read_b128 v[166:169], v237 offset:17408
	ds_read_b128 v[170:173], v237 offset:18432
	ds_read_b128 v[174:177], v237 offset:19456
	ds_read_b128 v[178:181], v237 offset:20480
	ds_read_b128 v[182:185], v237 offset:21504
	ds_read_b128 v[186:189], v237 offset:22528
	ds_read_b128 v[190:193], v237 offset:23552
	global_load_lds_dwordx4 v[194:195], off
	s_add_i32 m0, s55, 0x2000
	v_lshl_add_u64 v[196:197], s[58:59], 0, v[214:215]
	s_add_u32 s58, s58, s30
	s_addc_u32 s59, s59, s31
	s_add_i32 s55, vcc_lo, s36
	global_load_lds_dwordx4 v[196:197], off
	v_lshl_add_u64 v[198:199], s[58:59], 0, v[216:217]
	s_mov_b32 m0, s55
	v_lshl_add_u64 v[200:201], s[58:59], 0, v[214:215]
	global_load_lds_dwordx4 v[198:199], off
	s_add_i32 m0, s55, 0x2000
	v_lshl_add_u64 v[202:203], s[14:15], 0, v[210:211]
	global_load_lds_dwordx4 v[200:201], off
	s_mov_b32 m0, s51
	s_nop 0
	global_load_lds_dwordx4 v[202:203], off
	v_lshl_add_u64 v[202:203], s[14:15], 0, v[212:213]
	s_mov_b32 m0, s43
	s_nop 0
	global_load_lds_dwordx4 v[202:203], off
	s_waitcnt vmcnt(8)
	s_waitcnt lgkmcnt(0)
	s_barrier
	s_waitcnt lgkmcnt(0)
	v_mfma_f32_16x16x32_bf16 v[60:63], v[130:133], v[162:165], v[60:63]
	v_mfma_f32_16x16x32_bf16 v[60:63], v[134:137], v[166:169], v[60:63]
	v_mfma_f32_16x16x32_bf16 v[56:59], v[142:145], v[166:169], v[56:59]
	v_mfma_f32_16x16x32_bf16 v[56:59], v[138:141], v[162:165], v[56:59]
	v_mfma_f32_16x16x32_bf16 v[52:55], v[146:149], v[162:165], v[52:55]
	v_mfma_f32_16x16x32_bf16 v[52:55], v[150:153], v[166:169], v[52:55]
	v_mfma_f32_16x16x32_bf16 v[48:51], v[158:161], v[166:169], v[48:51]
	v_mfma_f32_16x16x32_bf16 v[48:51], v[154:157], v[162:165], v[48:51]
	v_mfma_f32_16x16x32_bf16 v[32:35], v[154:157], v[170:173], v[32:35]
	v_mfma_f32_16x16x32_bf16 v[32:35], v[158:161], v[174:177], v[32:35]
	v_mfma_f32_16x16x32_bf16 v[36:39], v[150:153], v[174:177], v[36:39]
	v_mfma_f32_16x16x32_bf16 v[36:39], v[146:149], v[170:173], v[36:39]
	v_mfma_f32_16x16x32_bf16 v[40:43], v[138:141], v[170:173], v[40:43]
	v_mfma_f32_16x16x32_bf16 v[40:43], v[142:145], v[174:177], v[40:43]
	v_mfma_f32_16x16x32_bf16 v[44:47], v[134:137], v[174:177], v[44:47]
	v_mfma_f32_16x16x32_bf16 v[44:47], v[130:133], v[170:173], v[44:47]
	v_mfma_f32_16x16x32_bf16 v[28:31], v[130:133], v[178:181], v[28:31]
	v_mfma_f32_16x16x32_bf16 v[28:31], v[134:137], v[182:185], v[28:31]
	v_mfma_f32_16x16x32_bf16 v[24:27], v[142:145], v[182:185], v[24:27]
	v_mfma_f32_16x16x32_bf16 v[24:27], v[138:141], v[178:181], v[24:27]
	v_mfma_f32_16x16x32_bf16 v[20:23], v[146:149], v[178:181], v[20:23]
	v_mfma_f32_16x16x32_bf16 v[20:23], v[150:153], v[182:185], v[20:23]
	v_mfma_f32_16x16x32_bf16 v[16:19], v[158:161], v[182:185], v[16:19]
	v_mfma_f32_16x16x32_bf16 v[16:19], v[154:157], v[178:181], v[16:19]
	v_mfma_f32_16x16x32_bf16 v[0:3], v[154:157], v[186:189], v[0:3]
	v_mfma_f32_16x16x32_bf16 v[0:3], v[158:161], v[190:193], v[0:3]
	v_mfma_f32_16x16x32_bf16 v[4:7], v[150:153], v[190:193], v[4:7]
	v_mfma_f32_16x16x32_bf16 v[4:7], v[146:149], v[186:189], v[4:7]
	v_mfma_f32_16x16x32_bf16 v[8:11], v[138:141], v[186:189], v[8:11]
	v_mfma_f32_16x16x32_bf16 v[8:11], v[142:145], v[190:193], v[8:11]
	v_mfma_f32_16x16x32_bf16 v[12:15], v[134:137], v[190:193], v[12:15]
	v_mfma_f32_16x16x32_bf16 v[12:15], v[130:133], v[186:189], v[12:15]
	s_barrier
.Lk_p2:
	s_add_i32 s55, 0, 0x18000
	v_add_u32_e32 v96, s55, v252
	s_add_i32 s58, 0, 0x1c000
	ds_read_b128 v[130:133], v96
	ds_read_b128 v[134:137], v96 offset:1024
	ds_read_b128 v[138:141], v96 offset:2048
	ds_read_b128 v[142:145], v96 offset:3072
	v_add_u32_e32 v96, s58, v252
	ds_read_b128 v[146:149], v96
	ds_read_b128 v[150:153], v96 offset:1024
	ds_read_b128 v[154:157], v96 offset:2048
	ds_read_b128 v[158:161], v96 offset:3072
	s_add_u32 s14, s14, s28
	s_addc_u32 s15, s15, s29
	s_mov_b32 m0, s40
	v_lshl_add_u64 v[202:203], s[14:15], 0, v[210:211]
	ds_read_b128 v[162:165], v237 offset:32768
	ds_read_b128 v[166:169], v237 offset:33792
	ds_read_b128 v[170:173], v237 offset:34816
	ds_read_b128 v[174:177], v237 offset:35840
	ds_read_b128 v[178:181], v237 offset:36864
	ds_read_b128 v[182:185], v237 offset:37888
	ds_read_b128 v[186:189], v237 offset:38912
	ds_read_b128 v[190:193], v237 offset:39936
	global_load_lds_dwordx4 v[202:203], off
	v_lshl_add_u64 v[202:203], s[14:15], 0, v[212:213]
	s_mov_b32 m0, s37
	s_nop 0
	global_load_lds_dwordx4 v[202:203], off
	s_waitcnt vmcnt(8)
	s_waitcnt lgkmcnt(0)
	s_barrier
; #define PG8_STAGE(bufoff, gbase, voff) do { _Pragma("unroll") for (int _i = 0; _i < 2; ++_i) \
;     __builtin_amdgcn_global_load_lds((const unsigned*)((const char*)(gbase) + (voff)[_i]), (LAS unsigned*)(lds + (bufoff) + ldsw + _i * 8192), 16, 0, 0); } while (0)
; #define PG8_LDA(dst, b, h) do { _Pragma("unroll") for (int m = 0; m < 4; ++m) _Pragma("unroll") for (int k = 0; k < 2; ++k) dst[m][k] = *(const LAS bf16x8*)(lds + PG8_SA(b, h) + aoff + m * 2048 + k * 1024); } while (0)
; #define PG8_LDB(dst, b, h) do { _Pragma("unroll") for (int n = 0; n < 2; ++n) _Pragma("unroll") for (int k = 0; k < 2; ++k) dst[n][k] = *(const LAS bf16x8*)(lds + PG8_SB(b, h) + boff + n * 2048 + k * 1024); } while (0)
; #define PG8_MMA(ai, bj, At, Bt) do { __builtin_amdgcn_s_setprio(1); _Pragma("unroll") for (int m = 0; m < 4; ++m) _Pragma("unroll") for (int n = 0; n < 2; ++n) _Pragma("unroll") for (int k = 0; k < 2; ++k) \
;     acc[ai][bj][m][n] = __builtin_amdgcn_mfma_f32_16x16x32_bf16(Bt[n][k], At[m][k], acc[ai][bj][m][n], 0, 0, 0); __builtin_amdgcn_s_setprio(0); } while (0)
; #define PG8_WAIT_V(n) asm volatile("s_waitcnt vmcnt(" #n ")" ::: "memory")
; #define PG8_WAIT_L(n) asm volatile("s_waitcnt lgkmcnt(" #n ")" ::: "memory")
; #define PG8_BAR __builtin_amdgcn_s_barrier()
; #define PG8_SCHED __builtin_amdgcn_sched_barrier(0)
; __device__ __forceinline__ void gemm_phase(const Ctx& cx, LAS unsigned char* lds, const GemmDesc& g) {
;     ...
;       PG8_LDB(B0, 1, 0); PG8_LDB(B1, 1, 1); PG8_SCHED; PG8_LDA(At, 1, 0); PG8_STAGE(PG8_SA(0, 1), a2 + hstepA, voffA);
;       PG8_WAIT_V(8); PG8_WAIT_L(0); PG8_BAR; PG8_MMA(0, 0, At, B0); PG8_MMA(0, 1, At, B1); PG8_BAR; PG8_SCHED;
;       PG8_LDA(At, 1, 1); PG8_STAGE(PG8_SB(1, 0), b3, voffB); PG8_STAGE(PG8_SB(1, 1), b3 + hstepB, voffB); PG8_STAGE(PG8_SA(1, 0), a3, voffA);
;       PG8_WAIT_V(8); PG8_WAIT_L(0); PG8_BAR; PG8_MMA(1, 0, At, B0); PG8_MMA(1, 1, At, B1); PG8_BAR; PG8_SCHED;
;     }
;     if (wr == 0) PG8_BAR;
	s_waitcnt lgkmcnt(0)
	v_mfma_f32_16x16x32_bf16 v[126:129], v[130:133], v[162:165], v[126:129]
	v_mfma_f32_16x16x32_bf16 v[126:129], v[134:137], v[166:169], v[126:129]
	v_mfma_f32_16x16x32_bf16 v[122:125], v[142:145], v[166:169], v[122:125]
	v_mfma_f32_16x16x32_bf16 v[122:125], v[138:141], v[162:165], v[122:125]
	v_mfma_f32_16x16x32_bf16 v[118:121], v[146:149], v[162:165], v[118:121]
	v_mfma_f32_16x16x32_bf16 v[118:121], v[150:153], v[166:169], v[118:121]
	v_mfma_f32_16x16x32_bf16 v[114:117], v[158:161], v[166:169], v[114:117]
	v_mfma_f32_16x16x32_bf16 v[114:117], v[154:157], v[162:165], v[114:117]
	v_mfma_f32_16x16x32_bf16 v[98:101], v[154:157], v[170:173], v[98:101]
	v_mfma_f32_16x16x32_bf16 v[98:101], v[158:161], v[174:177], v[98:101]
	v_mfma_f32_16x16x32_bf16 v[102:105], v[150:153], v[174:177], v[102:105]
	v_mfma_f32_16x16x32_bf16 v[102:105], v[146:149], v[170:173], v[102:105]
	v_mfma_f32_16x16x32_bf16 v[106:109], v[138:141], v[170:173], v[106:109]
	v_mfma_f32_16x16x32_bf16 v[106:109], v[142:145], v[174:177], v[106:109]
	v_mfma_f32_16x16x32_bf16 v[110:113], v[134:137], v[174:177], v[110:113]
	v_mfma_f32_16x16x32_bf16 v[110:113], v[130:133], v[170:173], v[110:113]
	v_mfma_f32_16x16x32_bf16 v[92:95], v[130:133], v[178:181], v[92:95]
	v_mfma_f32_16x16x32_bf16 v[92:95], v[134:137], v[182:185], v[92:95]
	v_mfma_f32_16x16x32_bf16 v[88:91], v[142:145], v[182:185], v[88:91]
	v_mfma_f32_16x16x32_bf16 v[88:91], v[138:141], v[178:181], v[88:91]
	v_mfma_f32_16x16x32_bf16 v[84:87], v[146:149], v[178:181], v[84:87]
	v_mfma_f32_16x16x32_bf16 v[84:87], v[150:153], v[182:185], v[84:87]
	v_mfma_f32_16x16x32_bf16 v[80:83], v[158:161], v[182:185], v[80:83]
	v_mfma_f32_16x16x32_bf16 v[80:83], v[154:157], v[178:181], v[80:83]
	v_mfma_f32_16x16x32_bf16 v[64:67], v[154:157], v[186:189], v[64:67]
	v_mfma_f32_16x16x32_bf16 v[64:67], v[158:161], v[190:193], v[64:67]
	v_mfma_f32_16x16x32_bf16 v[68:71], v[150:153], v[190:193], v[68:71]
	v_mfma_f32_16x16x32_bf16 v[68:71], v[146:149], v[186:189], v[68:71]
	v_mfma_f32_16x16x32_bf16 v[72:75], v[138:141], v[186:189], v[72:75]
	v_mfma_f32_16x16x32_bf16 v[72:75], v[142:145], v[190:193], v[72:75]
	v_mfma_f32_16x16x32_bf16 v[76:79], v[134:137], v[190:193], v[76:79]
	v_mfma_f32_16x16x32_bf16 v[76:79], v[130:133], v[186:189], v[76:79]
	s_barrier
	s_add_i32 s14, s55, s36
	v_lshl_add_u64 v[194:195], v[194:195], 0, s[92:93]
	s_mov_b32 m0, s14
	ds_read_b128 v[162:165], v237 offset:49152
	ds_read_b128 v[166:169], v237 offset:50176
	ds_read_b128 v[170:173], v237 offset:51200
	ds_read_b128 v[174:177], v237 offset:52224
	ds_read_b128 v[178:181], v237 offset:53248
	ds_read_b128 v[182:185], v237 offset:54272
	ds_read_b128 v[186:189], v237 offset:55296
	ds_read_b128 v[190:193], v237 offset:56320
	global_load_lds_dwordx4 v[194:195], off
	v_lshl_add_u64 v[194:195], v[196:197], 0, s[92:93]
	s_add_i32 m0, s14, 0x2000
	s_add_i32 s14, s58, s36
	global_load_lds_dwordx4 v[194:195], off
	v_lshl_add_u64 v[194:195], v[198:199], 0, s[92:93]
	s_mov_b32 m0, s14
	s_nop 0
	global_load_lds_dwordx4 v[194:195], off
	v_lshl_add_u64 v[194:195], v[200:201], 0, s[92:93]
	s_add_i32 m0, s14, 0x2000
	s_nop 0
	global_load_lds_dwordx4 v[194:195], off
	v_lshl_add_u64 v[194:195], s[6:7], 0, v[210:211]
	s_mov_b32 m0, s0
	s_nop 0
	global_load_lds_dwordx4 v[194:195], off
	v_lshl_add_u64 v[194:195], s[6:7], 0, v[212:213]
	s_mov_b32 m0, s1
	s_nop 0
	global_load_lds_dwordx4 v[194:195], off
	s_waitcnt vmcnt(8)
	s_waitcnt lgkmcnt(0)
	s_barrier
	s_waitcnt lgkmcnt(0)
	v_mfma_f32_16x16x32_bf16 v[60:63], v[130:133], v[162:165], v[60:63]
	v_mfma_f32_16x16x32_bf16 v[60:63], v[134:137], v[166:169], v[60:63]
	v_mfma_f32_16x16x32_bf16 v[56:59], v[142:145], v[166:169], v[56:59]
	v_mfma_f32_16x16x32_bf16 v[56:59], v[138:141], v[162:165], v[56:59]
	v_mfma_f32_16x16x32_bf16 v[52:55], v[146:149], v[162:165], v[52:55]
	v_mfma_f32_16x16x32_bf16 v[52:55], v[150:153], v[166:169], v[52:55]
	v_mfma_f32_16x16x32_bf16 v[48:51], v[158:161], v[166:169], v[48:51]
	v_mfma_f32_16x16x32_bf16 v[48:51], v[154:157], v[162:165], v[48:51]
	v_mfma_f32_16x16x32_bf16 v[32:35], v[154:157], v[170:173], v[32:35]
	v_mfma_f32_16x16x32_bf16 v[32:35], v[158:161], v[174:177], v[32:35]
	v_mfma_f32_16x16x32_bf16 v[36:39], v[150:153], v[174:177], v[36:39]
	v_mfma_f32_16x16x32_bf16 v[36:39], v[146:149], v[170:173], v[36:39]
	v_mfma_f32_16x16x32_bf16 v[40:43], v[138:141], v[170:173], v[40:43]
	v_mfma_f32_16x16x32_bf16 v[40:43], v[142:145], v[174:177], v[40:43]
	v_mfma_f32_16x16x32_bf16 v[44:47], v[134:137], v[174:177], v[44:47]
	v_mfma_f32_16x16x32_bf16 v[44:47], v[130:133], v[170:173], v[44:47]
	v_mfma_f32_16x16x32_bf16 v[28:31], v[130:133], v[178:181], v[28:31]
	v_mfma_f32_16x16x32_bf16 v[28:31], v[134:137], v[182:185], v[28:31]
	v_mfma_f32_16x16x32_bf16 v[24:27], v[142:145], v[182:185], v[24:27]
	v_mfma_f32_16x16x32_bf16 v[24:27], v[138:141], v[178:181], v[24:27]
	v_mfma_f32_16x16x32_bf16 v[20:23], v[146:149], v[178:181], v[20:23]
	v_mfma_f32_16x16x32_bf16 v[20:23], v[150:153], v[182:185], v[20:23]
	v_mfma_f32_16x16x32_bf16 v[16:19], v[158:161], v[182:185], v[16:19]
	v_mfma_f32_16x16x32_bf16 v[16:19], v[154:157], v[178:181], v[16:19]
	v_mfma_f32_16x16x32_bf16 v[0:3], v[154:157], v[186:189], v[0:3]
	v_mfma_f32_16x16x32_bf16 v[0:3], v[158:161], v[190:193], v[0:3]
	v_mfma_f32_16x16x32_bf16 v[4:7], v[150:153], v[190:193], v[4:7]
	v_mfma_f32_16x16x32_bf16 v[4:7], v[146:149], v[186:189], v[4:7]
	v_mfma_f32_16x16x32_bf16 v[8:11], v[138:141], v[186:189], v[8:11]
	v_mfma_f32_16x16x32_bf16 v[8:11], v[142:145], v[190:193], v[8:11]
	v_mfma_f32_16x16x32_bf16 v[12:15], v[134:137], v[190:193], v[12:15]
	v_mfma_f32_16x16x32_bf16 v[12:15], v[130:133], v[186:189], v[12:15]
	s_barrier
	s_add_u32 s52, s52, 0x100
	s_addc_u32 s53, s53, 0
	s_cmp_ge_u32 s54, s10
	s_mov_b32 s6, s54
	s_cbranch_scc0 .LBB0_358
	v_readlane_b32 s6, v255, 19
	v_readlane_b32 s7, v255, 20
	s_and_b64 vcc, exec, s[6:7]
	s_cbranch_vccz .LBB0_361
	s_barrier
